# own lean helper waves + 2x4 recurrence, chunk barrier doubled (second s_barrier right after the first)
# speedup vs baseline: 1.0213x; 1.0067x over previous
.LBB0_533:
	s_and_b64 vcc, exec, s[0:1]
	s_cbranch_vccz .LBB0_508
	v_mov_b32_e32 v57, v241
	s_ashr_i32 s48, s8, 5
	s_bfe_u32 s9, s8, 0x40001
	v_readfirstlane_b32 s0, v57
	s_and_b32 s10, s8, 1
	s_ashr_i32 s11, s0, 6
	s_ashr_i32 s49, s48, 31
	s_cmp_gt_i32 s11, 3
	s_mov_b64 s[0:1], -1
	s_cbranch_scc0 .LBB0_606
	s_waitcnt vmcnt(0)
	v_add_u32_e32 v198, 0xffffff00, v241
	v_lshrrev_b32_e32 v206, 3, v198
	v_and_b32_e32 v207, 7, v198
	s_lshl_b32 s0, s9, 6
	v_lshl_add_u32 v208, v207, 2, s0
	v_cmp_eq_u32_e64 s[38:39], 0, v207
	v_cmp_gt_u32_e64 s[28:29], 16, v206
	s_cmp_eq_u32 s10, 0
	s_cselect_b64 s[40:41], -1, 0
	s_nop 3
	s_and_b64 s[40:41], s[40:41], s[38:39]
	v_lshlrev_b32_e32 v199, 2, v208
	v_readlane_b32 s4, v255, 32
	v_readlane_b32 s5, v255, 33
	v_readlane_b32 s12, v255, 47
	v_readlane_b32 s13, v255, 48
	v_readlane_b32 s0, v255, 49
	v_readlane_b32 s1, v255, 50
	s_nop 4
	s_add_u32 s6, s4, 0x1000
	s_addc_u32 s7, s5, 0
	global_load_dwordx4 v[0:3], v199, s[4:5]
	global_load_dwordx4 v[4:7], v199, s[4:5] offset:128
	global_load_dwordx4 v[8:11], v199, s[6:7]
	global_load_dwordx4 v[12:15], v199, s[6:7] offset:128
	s_add_u32 s6, s4, 0x2000
	s_addc_u32 s7, s5, 0
	global_load_dwordx4 v[24:27], v199, s[12:13]
	global_load_dwordx4 v[28:31], v199, s[12:13] offset:128
	global_load_dwordx4 v[16:19], v199, s[6:7]
	global_load_dwordx4 v[20:23], v199, s[6:7] offset:128
	global_load_dwordx4 v[32:35], v199, s[0:1]
	global_load_dwordx4 v[36:39], v199, s[0:1] offset:128
	global_load_dwordx4 v[40:43], v199, s[64:65]
	global_load_dwordx4 v[44:47], v199, s[64:65] offset:128
	v_mov_b32_e32 v48, 0x3fb8aa3b
	v_mov_b32_e32 v49, 0x3fb8aa3b
	s_mul_i32 s0, s48, 0x810
	v_add_u32_e32 v209, s0, v206
	v_mov_b32_e32 v211, 0
	v_lshlrev_b32_e32 v210, 1, v208
	s_movk_i32 s14, 0x1a00
	v_mad_u64_u32 v[182:183], s[0:1], v209, s14, v[210:211]
	s_add_u32 s4, s86, 0x81a7000
	s_addc_u32 s5, s87, 0
	v_lshl_add_u64 v[182:183], v[182:183], 0, s[4:5]
	s_mov_b64 s[0:1], 0x1000
	v_lshl_add_u64 v[178:179], v[182:183], 0, s[0:1]
	v_lshl_add_u64 v[180:181], v[178:179], 0, s[0:1]
	v_lshl_add_u32 v198, v209, 11, v210
	v_mov_b32_e32 v210, v198
	s_add_u32 s4, s86, 0xeb48000
	s_addc_u32 s5, s87, 0
	v_lshl_add_u64 v[186:187], v[210:211], 0, s[4:5]
	s_add_u32 s4, s86, 0x10bc8000
	s_addc_u32 s5, s87, 0
	v_lshl_add_u64 v[188:189], v[210:211], 0, s[4:5]
	s_lshl_b32 s0, s9, 6
	s_lshl_b32 s1, s10, 5
	s_add_i32 s0, s0, s1
	v_lshl_add_u32 v198, v207, 2, s0
	v_lshlrev_b32_e32 v198, 1, v198
	v_lshl_add_u32 v210, v209, 11, v198
	s_add_u32 s4, s86, 0x5700000
	s_addc_u32 s5, s87, 0
	v_lshl_add_u64 v[190:191], v[210:211], 0, s[4:5]
	s_lshl_b32 s0, s9, 2
	v_lshl_add_u32 v210, v209, 6, s0
	s_add_u32 s4, s86, 0x7884000
	s_addc_u32 s5, s87, 0
	v_lshl_add_u64 v[192:193], v[210:211], 0, s[4:5]
	v_mul_u32_u24_e32 v194, 0x600, v206
	v_lshl_add_u32 v194, v207, 4, v194
	v_lshlrev_b32_e32 v195, 7, v206
	v_lshl_add_u32 v195, v207, 4, v195
	v_add_u32_e32 v195, 0x18000, v195
	v_lshlrev_b32_e32 v196, 2, v206
	v_add_u32_e32 v196, 0x1a000, v196
	v_lshlrev_b32_e32 v197, 3, v206
	v_add_u32_e32 v197, 0x1a100, v197
	global_load_dwordx2 v[52:53], v[178:179], off
	global_load_dwordx2 v[54:55], v[178:179], off offset:64
	global_load_dwordx2 v[56:57], v[178:179], off offset:2048
	global_load_dwordx2 v[58:59], v[178:179], off offset:2112
	global_load_dwordx2 v[60:61], v[180:181], off
	global_load_dwordx2 v[62:63], v[180:181], off offset:64
	global_load_dwordx2 v[64:65], v[182:183], off offset:-2560
	global_load_dwordx2 v[66:67], v[182:183], off offset:-2496
	global_load_dwordx2 v[68:69], v[182:183], off offset:-512
	global_load_dwordx2 v[70:71], v[182:183], off offset:-448
	global_load_dwordx2 v[72:73], v[178:179], off offset:-2560
	global_load_dwordx2 v[74:75], v[178:179], off offset:-2496
	global_load_dwordx2 v[76:77], v[186:187], off
	global_load_dwordx2 v[78:79], v[186:187], off offset:64
	global_load_dwordx2 v[80:81], v[188:189], off
	global_load_dwordx2 v[82:83], v[188:189], off offset:64
	s_mov_b32 s13, 0
	s_waitcnt vmcnt(0)
	v_cmp_ne_u32_e64 s[6:7], 0, v206
	s_nop 3
	v_cndmask_b32_e64 v64, 0, v64, s[6:7]
	v_cndmask_b32_e64 v65, 0, v65, s[6:7]
	v_cndmask_b32_e64 v66, 0, v66, s[6:7]
	v_cndmask_b32_e64 v67, 0, v67, s[6:7]
	v_cndmask_b32_e64 v68, 0, v68, s[6:7]
	v_cndmask_b32_e64 v69, 0, v69, s[6:7]
	v_cndmask_b32_e64 v70, 0, v70, s[6:7]
	v_cndmask_b32_e64 v71, 0, v71, s[6:7]
	v_cndmask_b32_e64 v72, 0, v72, s[6:7]
	v_cndmask_b32_e64 v73, 0, v73, s[6:7]
	v_cndmask_b32_e64 v74, 0, v74, s[6:7]
	v_cndmask_b32_e64 v75, 0, v75, s[6:7]
	v_lshlrev_b32_e32 v84, 16, v52
	v_and_b32_e32 v85, 0xffff0000, v52
	v_lshlrev_b32_e32 v86, 16, v53
	v_and_b32_e32 v87, 0xffff0000, v53
	v_lshlrev_b32_e32 v88, 16, v54
	v_and_b32_e32 v89, 0xffff0000, v54
	v_lshlrev_b32_e32 v90, 16, v55
	v_and_b32_e32 v91, 0xffff0000, v55
	v_lshlrev_b32_e32 v124, 16, v64
	v_and_b32_e32 v125, 0xffff0000, v64
	v_lshlrev_b32_e32 v126, 16, v65
	v_and_b32_e32 v127, 0xffff0000, v65
	v_lshlrev_b32_e32 v128, 16, v66
	v_and_b32_e32 v129, 0xffff0000, v66
	v_lshlrev_b32_e32 v130, 16, v67
	v_and_b32_e32 v131, 0xffff0000, v67
	v_pk_add_f32 v[124:125], v[124:125], v[84:85] neg_lo:[0,1] neg_hi:[0,1]
	v_pk_add_f32 v[126:127], v[126:127], v[86:87] neg_lo:[0,1] neg_hi:[0,1]
	v_pk_add_f32 v[128:129], v[128:129], v[88:89] neg_lo:[0,1] neg_hi:[0,1]
	v_pk_add_f32 v[130:131], v[130:131], v[90:91] neg_lo:[0,1] neg_hi:[0,1]
	v_pk_fma_f32 v[84:85], v[0:1], v[124:125], v[84:85]
	v_pk_fma_f32 v[86:87], v[2:3], v[126:127], v[86:87]
	v_pk_fma_f32 v[88:89], v[4:5], v[128:129], v[88:89]
	v_pk_fma_f32 v[90:91], v[6:7], v[130:131], v[90:91]
	v_lshlrev_b32_e32 v92, 16, v56
	v_and_b32_e32 v93, 0xffff0000, v56
	v_lshlrev_b32_e32 v94, 16, v57
	v_and_b32_e32 v95, 0xffff0000, v57
	v_lshlrev_b32_e32 v96, 16, v58
	v_and_b32_e32 v97, 0xffff0000, v58
	v_lshlrev_b32_e32 v98, 16, v59
	v_and_b32_e32 v99, 0xffff0000, v59
	v_lshlrev_b32_e32 v124, 16, v68
	v_and_b32_e32 v125, 0xffff0000, v68
	v_lshlrev_b32_e32 v126, 16, v69
	v_and_b32_e32 v127, 0xffff0000, v69
	v_lshlrev_b32_e32 v128, 16, v70
	v_and_b32_e32 v129, 0xffff0000, v70
	v_lshlrev_b32_e32 v130, 16, v71
	v_and_b32_e32 v131, 0xffff0000, v71
	v_pk_add_f32 v[124:125], v[124:125], v[92:93] neg_lo:[0,1] neg_hi:[0,1]
	v_pk_add_f32 v[126:127], v[126:127], v[94:95] neg_lo:[0,1] neg_hi:[0,1]
	v_pk_add_f32 v[128:129], v[128:129], v[96:97] neg_lo:[0,1] neg_hi:[0,1]
	v_pk_add_f32 v[130:131], v[130:131], v[98:99] neg_lo:[0,1] neg_hi:[0,1]
	v_pk_fma_f32 v[92:93], v[8:9], v[124:125], v[92:93]
	v_pk_fma_f32 v[94:95], v[10:11], v[126:127], v[94:95]
	v_pk_fma_f32 v[96:97], v[12:13], v[128:129], v[96:97]
	v_pk_fma_f32 v[98:99], v[14:15], v[130:131], v[98:99]
	v_lshlrev_b32_e32 v100, 16, v60
	v_and_b32_e32 v101, 0xffff0000, v60
	v_lshlrev_b32_e32 v102, 16, v61
	v_and_b32_e32 v103, 0xffff0000, v61
	v_lshlrev_b32_e32 v104, 16, v62
	v_and_b32_e32 v105, 0xffff0000, v62
	v_lshlrev_b32_e32 v106, 16, v63
	v_and_b32_e32 v107, 0xffff0000, v63
	v_lshlrev_b32_e32 v124, 16, v72
	v_and_b32_e32 v125, 0xffff0000, v72
	v_lshlrev_b32_e32 v126, 16, v73
	v_and_b32_e32 v127, 0xffff0000, v73
	v_lshlrev_b32_e32 v128, 16, v74
	v_and_b32_e32 v129, 0xffff0000, v74
	v_lshlrev_b32_e32 v130, 16, v75
	v_and_b32_e32 v131, 0xffff0000, v75
	v_pk_add_f32 v[124:125], v[124:125], v[100:101] neg_lo:[0,1] neg_hi:[0,1]
	v_pk_add_f32 v[126:127], v[126:127], v[102:103] neg_lo:[0,1] neg_hi:[0,1]
	v_pk_add_f32 v[128:129], v[128:129], v[104:105] neg_lo:[0,1] neg_hi:[0,1]
	v_pk_add_f32 v[130:131], v[130:131], v[106:107] neg_lo:[0,1] neg_hi:[0,1]
	v_pk_fma_f32 v[100:101], v[16:17], v[124:125], v[100:101]
	v_pk_fma_f32 v[102:103], v[18:19], v[126:127], v[102:103]
	v_pk_fma_f32 v[104:105], v[20:21], v[128:129], v[104:105]
	v_pk_fma_f32 v[106:107], v[22:23], v[130:131], v[106:107]
	v_lshlrev_b32_e32 v108, 16, v80
	v_and_b32_e32 v109, 0xffff0000, v80
	v_lshlrev_b32_e32 v110, 16, v81
	v_and_b32_e32 v111, 0xffff0000, v81
	v_lshlrev_b32_e32 v112, 16, v82
	v_and_b32_e32 v113, 0xffff0000, v82
	v_lshlrev_b32_e32 v114, 16, v83
	v_and_b32_e32 v115, 0xffff0000, v83
	v_lshlrev_b32_e32 v116, 16, v76
	v_and_b32_e32 v117, 0xffff0000, v76
	v_lshlrev_b32_e32 v118, 16, v77
	v_and_b32_e32 v119, 0xffff0000, v77
	v_lshlrev_b32_e32 v120, 16, v78
	v_and_b32_e32 v121, 0xffff0000, v78
	v_lshlrev_b32_e32 v122, 16, v79
	v_and_b32_e32 v123, 0xffff0000, v79
	v_pk_mul_f32 v[132:133], v[92:93], v[24:25]
	v_pk_mul_f32 v[134:135], v[94:95], v[26:27]
	v_pk_mul_f32 v[136:137], v[96:97], v[28:29]
	v_pk_mul_f32 v[138:139], v[98:99], v[30:31]
	v_pk_add_f32 v[124:125], v[108:109], -1.0 op_sel_hi:[1,0]
	v_pk_add_f32 v[126:127], v[110:111], -1.0 op_sel_hi:[1,0]
	v_pk_add_f32 v[128:129], v[112:113], -1.0 op_sel_hi:[1,0]
	v_pk_add_f32 v[130:131], v[114:115], -1.0 op_sel_hi:[1,0]
	v_pk_fma_f32 v[124:125], v[32:33], v[124:125], 1.0 op_sel_hi:[1,1,0]
	v_pk_fma_f32 v[126:127], v[34:35], v[126:127], 1.0 op_sel_hi:[1,1,0]
	v_pk_fma_f32 v[128:129], v[36:37], v[128:129], 1.0 op_sel_hi:[1,1,0]
	v_pk_fma_f32 v[130:131], v[38:39], v[130:131], 1.0 op_sel_hi:[1,1,0]
	v_pk_mul_f32 v[140:141], v[124:125], v[92:93]
	v_pk_mul_f32 v[142:143], v[126:127], v[94:95]
	v_pk_mul_f32 v[144:145], v[128:129], v[96:97]
	v_pk_mul_f32 v[146:147], v[130:131], v[98:99]
	v_pk_mul_f32 v[148:149], v[84:85], v[140:141]
	v_pk_mul_f32 v[150:151], v[86:87], v[142:143]
	v_pk_mul_f32 v[152:153], v[88:89], v[144:145]
	v_pk_mul_f32 v[154:155], v[90:91], v[146:147]
	v_pk_mul_f32 v[156:157], v[132:133], v[108:109]
	v_pk_mul_f32 v[158:159], v[134:135], v[110:111]
	v_pk_mul_f32 v[160:161], v[136:137], v[112:113]
	v_pk_mul_f32 v[162:163], v[138:139], v[114:115]
	v_pk_mul_f32 v[124:125], v[148:149], v[40:41]
	v_pk_mul_f32 v[126:127], v[150:151], v[42:43]
	v_pk_mul_f32 v[128:129], v[152:153], v[44:45]
	v_pk_mul_f32 v[130:131], v[154:155], v[46:47]
	v_pk_add_f32 v[124:125], v[124:125], v[126:127]
	v_pk_add_f32 v[128:129], v[128:129], v[130:131]
	v_pk_add_f32 v[124:125], v[124:125], v[128:129]
	v_add_f32_e32 v173, v124, v125
	v_pk_mul_f32 v[124:125], v[156:157], v[84:85]
	v_pk_mul_f32 v[126:127], v[158:159], v[86:87]
	v_pk_mul_f32 v[128:129], v[160:161], v[88:89]
	v_pk_mul_f32 v[130:131], v[162:163], v[90:91]
	v_pk_add_f32 v[124:125], v[124:125], v[126:127]
	v_pk_add_f32 v[128:129], v[128:129], v[130:131]
	v_pk_add_f32 v[124:125], v[124:125], v[128:129]
	v_add_f32_e32 v174, v124, v125
	v_pk_mul_f32 v[124:125], v[132:133], v[132:133]
	v_pk_mul_f32 v[126:127], v[134:135], v[134:135]
	v_pk_mul_f32 v[128:129], v[136:137], v[136:137]
	v_pk_mul_f32 v[130:131], v[138:139], v[138:139]
	v_pk_add_f32 v[124:125], v[124:125], v[126:127]
	v_pk_add_f32 v[128:129], v[128:129], v[130:131]
	v_pk_add_f32 v[124:125], v[124:125], v[128:129]
	v_add_f32_e32 v172, v124, v125
	v_pk_add_f32 v[148:149], v[148:149], v[150:151]
	v_pk_add_f32 v[152:153], v[152:153], v[154:155]
	v_pk_add_f32 v[148:149], v[148:149], v[152:153]
	v_add_f32_e32 v175, v148, v149
	v_pk_mul_f32 v[116:117], v[116:117], v[48:49]
	v_pk_mul_f32 v[118:119], v[118:119], v[48:49]
	v_pk_mul_f32 v[120:121], v[120:121], v[48:49]
	v_pk_mul_f32 v[122:123], v[122:123], v[48:49]
	v_add_f32_dpp v172, v172, v172 quad_perm:[1,0,3,2] row_mask:0xf bank_mask:0xf bound_ctrl:1
	v_add_f32_dpp v173, v173, v173 quad_perm:[1,0,3,2] row_mask:0xf bank_mask:0xf bound_ctrl:1
	v_add_f32_dpp v174, v174, v174 quad_perm:[1,0,3,2] row_mask:0xf bank_mask:0xf bound_ctrl:1
	v_add_f32_dpp v175, v175, v175 quad_perm:[1,0,3,2] row_mask:0xf bank_mask:0xf bound_ctrl:1
	v_add_f32_dpp v172, v172, v172 quad_perm:[2,3,0,1] row_mask:0xf bank_mask:0xf bound_ctrl:1
	v_add_f32_dpp v173, v173, v173 quad_perm:[2,3,0,1] row_mask:0xf bank_mask:0xf bound_ctrl:1
	v_add_f32_dpp v174, v174, v174 quad_perm:[2,3,0,1] row_mask:0xf bank_mask:0xf bound_ctrl:1
	v_add_f32_dpp v175, v175, v175 quad_perm:[2,3,0,1] row_mask:0xf bank_mask:0xf bound_ctrl:1
	v_add_f32_dpp v172, v172, v172 row_half_mirror row_mask:0xf bank_mask:0xf bound_ctrl:1
	v_add_f32_dpp v173, v173, v173 row_half_mirror row_mask:0xf bank_mask:0xf bound_ctrl:1
	v_add_f32_dpp v174, v174, v174 row_half_mirror row_mask:0xf bank_mask:0xf bound_ctrl:1
	v_add_f32_dpp v175, v175, v175 row_half_mirror row_mask:0xf bank_mask:0xf bound_ctrl:1
	v_exp_f32_e32 v116, v116
	v_exp_f32_e32 v117, v117
	v_exp_f32_e32 v118, v118
	v_exp_f32_e32 v119, v119
	v_exp_f32_e32 v120, v120
	v_exp_f32_e32 v121, v121
	v_exp_f32_e32 v122, v122
	v_exp_f32_e32 v123, v123
	v_rsq_f32_e32 v176, v172
	v_pk_mul_f32 v[148:149], v[116:117], v[84:85]
	v_pk_mul_f32 v[150:151], v[118:119], v[86:87]
	v_pk_mul_f32 v[152:153], v[120:121], v[88:89]
	v_pk_mul_f32 v[154:155], v[122:123], v[90:91]
	v_min_f32_e32 v176, 0x5368d4a5, v176
	v_mul_f32_e32 v174, v174, v176
	v_pk_mul_f32 v[164:165], v[132:133], v[176:177] op_sel_hi:[1,0] neg_lo:[1,0] neg_hi:[1,0]
	v_pk_mul_f32 v[166:167], v[134:135], v[176:177] op_sel_hi:[1,0] neg_lo:[1,0] neg_hi:[1,0]
	v_pk_mul_f32 v[168:169], v[136:137], v[176:177] op_sel_hi:[1,0] neg_lo:[1,0] neg_hi:[1,0]
	v_pk_mul_f32 v[170:171], v[138:139], v[176:177] op_sel_hi:[1,0] neg_lo:[1,0] neg_hi:[1,0]
	v_pk_mul_f32 v[156:157], v[156:157], v[176:177] op_sel_hi:[1,0]
	v_pk_mul_f32 v[158:159], v[158:159], v[176:177] op_sel_hi:[1,0]
	v_pk_mul_f32 v[160:161], v[160:161], v[176:177] op_sel_hi:[1,0]
	v_pk_mul_f32 v[162:163], v[162:163], v[176:177] op_sel_hi:[1,0]
	s_mul_i32 s14, s13, 0xc000
	v_add_u32_e32 v198, s14, v194
	ds_write_b128 v198, v[148:151] offset:0
	ds_write_b128 v198, v[152:155] offset:128
	ds_write_b128 v198, v[116:119] offset:256
	ds_write_b128 v198, v[120:123] offset:384
	ds_write_b128 v198, v[140:143] offset:512
	ds_write_b128 v198, v[144:147] offset:640
	ds_write_b128 v198, v[164:167] offset:768
	ds_write_b128 v198, v[168:171] offset:896
	ds_write_b128 v198, v[156:159] offset:1024
	ds_write_b128 v198, v[160:163] offset:1152
	ds_write_b128 v198, v[100:103] offset:1280
	ds_write_b128 v198, v[104:107] offset:1408
	s_lshl_b32 s14, s13, 7
	v_add_u32_e32 v199, s14, v196
	s_lshl_b32 s14, s13, 8
	v_add_u32_e32 v198, s14, v197
	ds_write_b32 v199, v173
	ds_write_b64 v198, v[174:175]
	s_mov_b64 s[0:1], 0x34000
	v_lshl_add_u64 v[178:179], v[178:179], 0, s[0:1]
	v_lshl_add_u64 v[180:181], v[180:181], 0, s[0:1]
	v_lshl_add_u64 v[182:183], v[182:183], 0, s[0:1]
	s_mov_b64 s[0:1], 0x10000
	v_lshl_add_u64 v[186:187], v[186:187], 0, s[0:1]
	v_lshl_add_u64 v[188:189], v[188:189], 0, s[0:1]
	global_load_dwordx2 v[52:53], v[178:179], off
	global_load_dwordx2 v[54:55], v[178:179], off offset:64
	global_load_dwordx2 v[56:57], v[178:179], off offset:2048
	global_load_dwordx2 v[58:59], v[178:179], off offset:2112
	global_load_dwordx2 v[60:61], v[180:181], off
	global_load_dwordx2 v[62:63], v[180:181], off offset:64
	global_load_dwordx2 v[64:65], v[182:183], off offset:-2560
	global_load_dwordx2 v[66:67], v[182:183], off offset:-2496
	global_load_dwordx2 v[68:69], v[182:183], off offset:-512
	global_load_dwordx2 v[70:71], v[182:183], off offset:-448
	global_load_dwordx2 v[72:73], v[178:179], off offset:-2560
	global_load_dwordx2 v[74:75], v[178:179], off offset:-2496
	global_load_dwordx2 v[76:77], v[186:187], off
	global_load_dwordx2 v[78:79], v[186:187], off offset:64
	global_load_dwordx2 v[80:81], v[188:189], off
	global_load_dwordx2 v[82:83], v[188:189], off offset:64
	s_waitcnt lgkmcnt(0)
	s_barrier
	s_mov_b32 s12, 0
.Lh_loop:
	s_cmp_eq_u32 s12, 0
	s_cbranch_scc1 .Lh_nopost
	s_add_i32 s13, s12, 1
	s_and_b32 s13, s13, 1
	s_lshl_b32 s14, s13, 12
	v_add_u32_e32 v198, s14, v195
	s_lshl_b32 s14, s13, 7
	v_add_u32_e32 v199, s14, v196
	ds_read_b128 v[200:203], v198
	ds_read_b32 v204, v199
	s_waitcnt lgkmcnt(0)
	v_cvt_pk_bf16_f32 v200, v200, v201
	v_cvt_pk_bf16_f32 v201, v202, v203
	global_store_dwordx2 v[190:191], v[200:201], off
	s_mov_b64 s[4:5], exec
	s_and_b64 exec, exec, s[40:41]
	s_cbranch_execz .Lh_nobeta_loop
	global_store_dword v[192:193], v204, off
.Lh_nobeta_loop:
	s_mov_b64 exec, s[4:5]
	s_mov_b64 s[0:1], 0x10000
	v_lshl_add_u64 v[190:191], v[190:191], 0, s[0:1]
	s_mov_b64 s[0:1], 0x800
	v_lshl_add_u64 v[192:193], v[192:193], 0, s[0:1]
.Lh_nopost:
	s_cmp_lt_u32 s12, 64
	s_cbranch_scc0 .Lh_nobuild
	s_add_i32 s13, s12, 1
	s_and_b32 s13, s13, 1
	s_waitcnt vmcnt(1)
	v_lshlrev_b32_e32 v84, 16, v52
	v_and_b32_e32 v85, 0xffff0000, v52
	v_lshlrev_b32_e32 v86, 16, v53
	v_and_b32_e32 v87, 0xffff0000, v53
	v_lshlrev_b32_e32 v88, 16, v54
	v_and_b32_e32 v89, 0xffff0000, v54
	v_lshlrev_b32_e32 v90, 16, v55
	v_and_b32_e32 v91, 0xffff0000, v55
	v_lshlrev_b32_e32 v124, 16, v64
	v_and_b32_e32 v125, 0xffff0000, v64
	v_lshlrev_b32_e32 v126, 16, v65
	v_and_b32_e32 v127, 0xffff0000, v65
	v_lshlrev_b32_e32 v128, 16, v66
	v_and_b32_e32 v129, 0xffff0000, v66
	v_lshlrev_b32_e32 v130, 16, v67
	v_and_b32_e32 v131, 0xffff0000, v67
	v_pk_add_f32 v[124:125], v[124:125], v[84:85] neg_lo:[0,1] neg_hi:[0,1]
	v_pk_add_f32 v[126:127], v[126:127], v[86:87] neg_lo:[0,1] neg_hi:[0,1]
	v_pk_add_f32 v[128:129], v[128:129], v[88:89] neg_lo:[0,1] neg_hi:[0,1]
	v_pk_add_f32 v[130:131], v[130:131], v[90:91] neg_lo:[0,1] neg_hi:[0,1]
	v_pk_fma_f32 v[84:85], v[0:1], v[124:125], v[84:85]
	v_pk_fma_f32 v[86:87], v[2:3], v[126:127], v[86:87]
	v_pk_fma_f32 v[88:89], v[4:5], v[128:129], v[88:89]
	v_pk_fma_f32 v[90:91], v[6:7], v[130:131], v[90:91]
	v_lshlrev_b32_e32 v92, 16, v56
	v_and_b32_e32 v93, 0xffff0000, v56
	v_lshlrev_b32_e32 v94, 16, v57
	v_and_b32_e32 v95, 0xffff0000, v57
	v_lshlrev_b32_e32 v96, 16, v58
	v_and_b32_e32 v97, 0xffff0000, v58
	v_lshlrev_b32_e32 v98, 16, v59
	v_and_b32_e32 v99, 0xffff0000, v59
	v_lshlrev_b32_e32 v124, 16, v68
	v_and_b32_e32 v125, 0xffff0000, v68
	v_lshlrev_b32_e32 v126, 16, v69
	v_and_b32_e32 v127, 0xffff0000, v69
	v_lshlrev_b32_e32 v128, 16, v70
	v_and_b32_e32 v129, 0xffff0000, v70
	v_lshlrev_b32_e32 v130, 16, v71
	v_and_b32_e32 v131, 0xffff0000, v71
	v_pk_add_f32 v[124:125], v[124:125], v[92:93] neg_lo:[0,1] neg_hi:[0,1]
	v_pk_add_f32 v[126:127], v[126:127], v[94:95] neg_lo:[0,1] neg_hi:[0,1]
	v_pk_add_f32 v[128:129], v[128:129], v[96:97] neg_lo:[0,1] neg_hi:[0,1]
	v_pk_add_f32 v[130:131], v[130:131], v[98:99] neg_lo:[0,1] neg_hi:[0,1]
	v_pk_fma_f32 v[92:93], v[8:9], v[124:125], v[92:93]
	v_pk_fma_f32 v[94:95], v[10:11], v[126:127], v[94:95]
	v_pk_fma_f32 v[96:97], v[12:13], v[128:129], v[96:97]
	v_pk_fma_f32 v[98:99], v[14:15], v[130:131], v[98:99]
	v_lshlrev_b32_e32 v100, 16, v60
	v_and_b32_e32 v101, 0xffff0000, v60
	v_lshlrev_b32_e32 v102, 16, v61
	v_and_b32_e32 v103, 0xffff0000, v61
	v_lshlrev_b32_e32 v104, 16, v62
	v_and_b32_e32 v105, 0xffff0000, v62
	v_lshlrev_b32_e32 v106, 16, v63
	v_and_b32_e32 v107, 0xffff0000, v63
	v_lshlrev_b32_e32 v124, 16, v72
	v_and_b32_e32 v125, 0xffff0000, v72
	v_lshlrev_b32_e32 v126, 16, v73
	v_and_b32_e32 v127, 0xffff0000, v73
	v_lshlrev_b32_e32 v128, 16, v74
	v_and_b32_e32 v129, 0xffff0000, v74
	v_lshlrev_b32_e32 v130, 16, v75
	v_and_b32_e32 v131, 0xffff0000, v75
	v_pk_add_f32 v[124:125], v[124:125], v[100:101] neg_lo:[0,1] neg_hi:[0,1]
	v_pk_add_f32 v[126:127], v[126:127], v[102:103] neg_lo:[0,1] neg_hi:[0,1]
	v_pk_add_f32 v[128:129], v[128:129], v[104:105] neg_lo:[0,1] neg_hi:[0,1]
	v_pk_add_f32 v[130:131], v[130:131], v[106:107] neg_lo:[0,1] neg_hi:[0,1]
	v_pk_fma_f32 v[100:101], v[16:17], v[124:125], v[100:101]
	v_pk_fma_f32 v[102:103], v[18:19], v[126:127], v[102:103]
	v_pk_fma_f32 v[104:105], v[20:21], v[128:129], v[104:105]
	v_pk_fma_f32 v[106:107], v[22:23], v[130:131], v[106:107]
	v_lshlrev_b32_e32 v108, 16, v80
	v_and_b32_e32 v109, 0xffff0000, v80
	v_lshlrev_b32_e32 v110, 16, v81
	v_and_b32_e32 v111, 0xffff0000, v81
	v_lshlrev_b32_e32 v112, 16, v82
	v_and_b32_e32 v113, 0xffff0000, v82
	v_lshlrev_b32_e32 v114, 16, v83
	v_and_b32_e32 v115, 0xffff0000, v83
	v_lshlrev_b32_e32 v116, 16, v76
	v_and_b32_e32 v117, 0xffff0000, v76
	v_lshlrev_b32_e32 v118, 16, v77
	v_and_b32_e32 v119, 0xffff0000, v77
	v_lshlrev_b32_e32 v120, 16, v78
	v_and_b32_e32 v121, 0xffff0000, v78
	v_lshlrev_b32_e32 v122, 16, v79
	v_and_b32_e32 v123, 0xffff0000, v79
	v_pk_mul_f32 v[132:133], v[92:93], v[24:25]
	v_pk_mul_f32 v[134:135], v[94:95], v[26:27]
	v_pk_mul_f32 v[136:137], v[96:97], v[28:29]
	v_pk_mul_f32 v[138:139], v[98:99], v[30:31]
	v_pk_add_f32 v[124:125], v[108:109], -1.0 op_sel_hi:[1,0]
	v_pk_add_f32 v[126:127], v[110:111], -1.0 op_sel_hi:[1,0]
	v_pk_add_f32 v[128:129], v[112:113], -1.0 op_sel_hi:[1,0]
	v_pk_add_f32 v[130:131], v[114:115], -1.0 op_sel_hi:[1,0]
	v_pk_fma_f32 v[124:125], v[32:33], v[124:125], 1.0 op_sel_hi:[1,1,0]
	v_pk_fma_f32 v[126:127], v[34:35], v[126:127], 1.0 op_sel_hi:[1,1,0]
	v_pk_fma_f32 v[128:129], v[36:37], v[128:129], 1.0 op_sel_hi:[1,1,0]
	v_pk_fma_f32 v[130:131], v[38:39], v[130:131], 1.0 op_sel_hi:[1,1,0]
	v_pk_mul_f32 v[140:141], v[124:125], v[92:93]
	v_pk_mul_f32 v[142:143], v[126:127], v[94:95]
	v_pk_mul_f32 v[144:145], v[128:129], v[96:97]
	v_pk_mul_f32 v[146:147], v[130:131], v[98:99]
	v_pk_mul_f32 v[148:149], v[84:85], v[140:141]
	v_pk_mul_f32 v[150:151], v[86:87], v[142:143]
	v_pk_mul_f32 v[152:153], v[88:89], v[144:145]
	v_pk_mul_f32 v[154:155], v[90:91], v[146:147]
	v_pk_mul_f32 v[156:157], v[132:133], v[108:109]
	v_pk_mul_f32 v[158:159], v[134:135], v[110:111]
	v_pk_mul_f32 v[160:161], v[136:137], v[112:113]
	v_pk_mul_f32 v[162:163], v[138:139], v[114:115]
	v_pk_mul_f32 v[124:125], v[148:149], v[40:41]
	v_pk_mul_f32 v[126:127], v[150:151], v[42:43]
	v_pk_mul_f32 v[128:129], v[152:153], v[44:45]
	v_pk_mul_f32 v[130:131], v[154:155], v[46:47]
	v_pk_add_f32 v[124:125], v[124:125], v[126:127]
	v_pk_add_f32 v[128:129], v[128:129], v[130:131]
	v_pk_add_f32 v[124:125], v[124:125], v[128:129]
	v_add_f32_e32 v173, v124, v125
	v_pk_mul_f32 v[124:125], v[156:157], v[84:85]
	v_pk_mul_f32 v[126:127], v[158:159], v[86:87]
	v_pk_mul_f32 v[128:129], v[160:161], v[88:89]
	v_pk_mul_f32 v[130:131], v[162:163], v[90:91]
	v_pk_add_f32 v[124:125], v[124:125], v[126:127]
	v_pk_add_f32 v[128:129], v[128:129], v[130:131]
	v_pk_add_f32 v[124:125], v[124:125], v[128:129]
	v_add_f32_e32 v174, v124, v125
	v_pk_mul_f32 v[124:125], v[132:133], v[132:133]
	v_pk_mul_f32 v[126:127], v[134:135], v[134:135]
	v_pk_mul_f32 v[128:129], v[136:137], v[136:137]
	v_pk_mul_f32 v[130:131], v[138:139], v[138:139]
	v_pk_add_f32 v[124:125], v[124:125], v[126:127]
	v_pk_add_f32 v[128:129], v[128:129], v[130:131]
	v_pk_add_f32 v[124:125], v[124:125], v[128:129]
	v_add_f32_e32 v172, v124, v125
	v_pk_add_f32 v[148:149], v[148:149], v[150:151]
	v_pk_add_f32 v[152:153], v[152:153], v[154:155]
	v_pk_add_f32 v[148:149], v[148:149], v[152:153]
	v_add_f32_e32 v175, v148, v149
	v_pk_mul_f32 v[116:117], v[116:117], v[48:49]
	v_pk_mul_f32 v[118:119], v[118:119], v[48:49]
	v_pk_mul_f32 v[120:121], v[120:121], v[48:49]
	v_pk_mul_f32 v[122:123], v[122:123], v[48:49]
	v_add_f32_dpp v172, v172, v172 quad_perm:[1,0,3,2] row_mask:0xf bank_mask:0xf bound_ctrl:1
	v_add_f32_dpp v173, v173, v173 quad_perm:[1,0,3,2] row_mask:0xf bank_mask:0xf bound_ctrl:1
	v_add_f32_dpp v174, v174, v174 quad_perm:[1,0,3,2] row_mask:0xf bank_mask:0xf bound_ctrl:1
	v_add_f32_dpp v175, v175, v175 quad_perm:[1,0,3,2] row_mask:0xf bank_mask:0xf bound_ctrl:1
	v_add_f32_dpp v172, v172, v172 quad_perm:[2,3,0,1] row_mask:0xf bank_mask:0xf bound_ctrl:1
	v_add_f32_dpp v173, v173, v173 quad_perm:[2,3,0,1] row_mask:0xf bank_mask:0xf bound_ctrl:1
	v_add_f32_dpp v174, v174, v174 quad_perm:[2,3,0,1] row_mask:0xf bank_mask:0xf bound_ctrl:1
	v_add_f32_dpp v175, v175, v175 quad_perm:[2,3,0,1] row_mask:0xf bank_mask:0xf bound_ctrl:1
	v_add_f32_dpp v172, v172, v172 row_half_mirror row_mask:0xf bank_mask:0xf bound_ctrl:1
	v_add_f32_dpp v173, v173, v173 row_half_mirror row_mask:0xf bank_mask:0xf bound_ctrl:1
	v_add_f32_dpp v174, v174, v174 row_half_mirror row_mask:0xf bank_mask:0xf bound_ctrl:1
	v_add_f32_dpp v175, v175, v175 row_half_mirror row_mask:0xf bank_mask:0xf bound_ctrl:1
	v_exp_f32_e32 v116, v116
	v_exp_f32_e32 v117, v117
	v_exp_f32_e32 v118, v118
	v_exp_f32_e32 v119, v119
	v_exp_f32_e32 v120, v120
	v_exp_f32_e32 v121, v121
	v_exp_f32_e32 v122, v122
	v_exp_f32_e32 v123, v123
	v_rsq_f32_e32 v176, v172
	v_pk_mul_f32 v[148:149], v[116:117], v[84:85]
	v_pk_mul_f32 v[150:151], v[118:119], v[86:87]
	v_pk_mul_f32 v[152:153], v[120:121], v[88:89]
	v_pk_mul_f32 v[154:155], v[122:123], v[90:91]
	v_min_f32_e32 v176, 0x5368d4a5, v176
	v_mul_f32_e32 v174, v174, v176
	v_pk_mul_f32 v[164:165], v[132:133], v[176:177] op_sel_hi:[1,0] neg_lo:[1,0] neg_hi:[1,0]
	v_pk_mul_f32 v[166:167], v[134:135], v[176:177] op_sel_hi:[1,0] neg_lo:[1,0] neg_hi:[1,0]
	v_pk_mul_f32 v[168:169], v[136:137], v[176:177] op_sel_hi:[1,0] neg_lo:[1,0] neg_hi:[1,0]
	v_pk_mul_f32 v[170:171], v[138:139], v[176:177] op_sel_hi:[1,0] neg_lo:[1,0] neg_hi:[1,0]
	v_pk_mul_f32 v[156:157], v[156:157], v[176:177] op_sel_hi:[1,0]
	v_pk_mul_f32 v[158:159], v[158:159], v[176:177] op_sel_hi:[1,0]
	v_pk_mul_f32 v[160:161], v[160:161], v[176:177] op_sel_hi:[1,0]
	v_pk_mul_f32 v[162:163], v[162:163], v[176:177] op_sel_hi:[1,0]
	s_mul_i32 s14, s13, 0xc000
	v_add_u32_e32 v198, s14, v194
	ds_write_b128 v198, v[148:151] offset:0
	ds_write_b128 v198, v[152:155] offset:128
	ds_write_b128 v198, v[116:119] offset:256
	ds_write_b128 v198, v[120:123] offset:384
	ds_write_b128 v198, v[140:143] offset:512
	ds_write_b128 v198, v[144:147] offset:640
	ds_write_b128 v198, v[164:167] offset:768
	ds_write_b128 v198, v[168:171] offset:896
	ds_write_b128 v198, v[156:159] offset:1024
	ds_write_b128 v198, v[160:163] offset:1152
	ds_write_b128 v198, v[100:103] offset:1280
	ds_write_b128 v198, v[104:107] offset:1408
	s_lshl_b32 s14, s13, 7
	v_add_u32_e32 v199, s14, v196
	s_lshl_b32 s14, s13, 8
	v_add_u32_e32 v198, s14, v197
	ds_write_b32 v199, v173
	ds_write_b64 v198, v[174:175]
	s_cmp_lt_u32 s12, 63
	s_cbranch_scc0 .Lh_nobuild
	s_mov_b64 s[0:1], 0x34000
	v_lshl_add_u64 v[178:179], v[178:179], 0, s[0:1]
	v_lshl_add_u64 v[180:181], v[180:181], 0, s[0:1]
	v_lshl_add_u64 v[182:183], v[182:183], 0, s[0:1]
	s_mov_b64 s[0:1], 0x10000
	v_lshl_add_u64 v[186:187], v[186:187], 0, s[0:1]
	v_lshl_add_u64 v[188:189], v[188:189], 0, s[0:1]
	global_load_dwordx2 v[52:53], v[178:179], off
	global_load_dwordx2 v[54:55], v[178:179], off offset:64
	global_load_dwordx2 v[56:57], v[178:179], off offset:2048
	global_load_dwordx2 v[58:59], v[178:179], off offset:2112
	global_load_dwordx2 v[60:61], v[180:181], off
	global_load_dwordx2 v[62:63], v[180:181], off offset:64
	global_load_dwordx2 v[64:65], v[182:183], off offset:-2560
	global_load_dwordx2 v[66:67], v[182:183], off offset:-2496
	global_load_dwordx2 v[68:69], v[182:183], off offset:-512
	global_load_dwordx2 v[70:71], v[182:183], off offset:-448
	global_load_dwordx2 v[72:73], v[178:179], off offset:-2560
	global_load_dwordx2 v[74:75], v[178:179], off offset:-2496
	global_load_dwordx2 v[76:77], v[186:187], off
	global_load_dwordx2 v[78:79], v[186:187], off offset:64
	global_load_dwordx2 v[80:81], v[188:189], off
	global_load_dwordx2 v[82:83], v[188:189], off offset:64
.Lh_nobuild:
	s_waitcnt lgkmcnt(0)
	s_barrier
	s_barrier
	s_add_i32 s12, s12, 1
	s_cmp_lt_u32 s12, 0x41
	s_cbranch_scc1 .Lh_loop
	s_mov_b32 s13, 0
	s_and_saveexec_b64 s[6:7], s[28:29]
	s_cbranch_execz .Lh_post_skip_last
	s_lshl_b32 s14, s13, 12
	v_add_u32_e32 v198, s14, v195
	s_lshl_b32 s14, s13, 7
	v_add_u32_e32 v199, s14, v196
	ds_read_b128 v[200:203], v198
	ds_read_b32 v204, v199
	s_waitcnt lgkmcnt(0)
	v_cvt_pk_bf16_f32 v200, v200, v201
	v_cvt_pk_bf16_f32 v201, v202, v203
	global_store_dwordx2 v[190:191], v[200:201], off
	s_mov_b64 s[4:5], exec
	s_and_b64 exec, exec, s[40:41]
	s_cbranch_execz .Lh_nobeta_last
	global_store_dword v[192:193], v204, off
.Lh_nobeta_last:
	s_mov_b64 exec, s[4:5]
.Lh_post_skip_last:
	s_mov_b64 exec, s[6:7]
	s_branch .LBB0_508

.Lrec_chunk_end:
	s_waitcnt lgkmcnt(0)
	s_barrier
	s_barrier
	s_add_i32 s4, s4, 1
	s_cmpk_lg_i32 s4, 0x41
	s_cbranch_scc1 .Lrec_chunk
	s_lshl_b64 s[0:1], s[48:49], 4
	v_readlane_b32 s4, v255, 43
	v_readlane_b32 s5, v255, 44
	v_mov_b32_e32 v90, v0
	v_mov_b32_e32 v91, v2
	s_add_u32 s0, s0, s4
	s_addc_u32 s1, s1, s5
	s_or_b32 s0, s0, s9
	s_lshl_b64 s[0:1], s[0:1], 14
	v_readlane_b32 s4, v252, 33
	v_readlane_b32 s5, v252, 34
	v_mov_b32_e32 v92, v4
	v_mov_b32_e32 v93, v6
	v_mov_b32_e32 v94, v1
	v_mov_b32_e32 v95, v3
	s_add_u32 s0, s4, s0
	s_addc_u32 s1, s5, s1
	v_mov_b32_e32 v96, v5
	v_mov_b32_e32 v97, v7
	v_lshl_add_u32 v98, v87, 6, v86
	v_lshl_add_u32 v99, v88, 6, v86
	s_nop 1
	global_store_dwordx4 v98, v[90:93], s[0:1]
	global_store_dwordx4 v99, v[94:97], s[0:1]
	s_branch .LBB0_508
